# v26 + SwiGLU GEMM: wave halves no longer align their epilogues (leading half's epilogue overlaps the other half's last MFMA phase)
# baseline (speedup 1.0000x reference)
; #define PG8_STAGE(bufoff, gbase, voff) do { _Pragma("unroll") for (int _i = 0; _i < 2; ++_i) \
;         __builtin_amdgcn_global_load_lds((const unsigned*)((const char*)(gbase) + (voff)[_i]), (LAS unsigned*)(lds + (bufoff) + ldsw + _i * 8192), 16, 0, 0); } while (0)
; #define PG8_LDA(dst, b, h) do { _Pragma("unroll") for (int m = 0; m < 4; ++m) _Pragma("unroll") for (int k = 0; k < 2; ++k) dst[m][k] = *(const LAS bf16x8*)(lds + PG8_SA(b, h) + aoff + m * 2048 + k * 1024); } while (0)
; #define PG8_LDB(dst, b, h) do { _Pragma("unroll") for (int n = 0; n < 2; ++n) _Pragma("unroll") for (int k = 0; k < 2; ++k) dst[n][k] = *(const LAS bf16x8*)(lds + PG8_SB(b, h) + boff + n * 2048 + k * 1024); } while (0)
; #define PG8_MMA(ai, bj, At, Bt) do { __builtin_amdgcn_s_setprio(1); _Pragma("unroll") for (int m = 0; m < 4; ++m) _Pragma("unroll") for (int n = 0; n < 2; ++n) _Pragma("unroll") for (int k = 0; k < 2; ++k) \
;         acc[ai][bj][m][n] = __builtin_amdgcn_mfma_f32_16x16x32_bf16(Bt[n][k], At[m][k], acc[ai][bj][m][n], 0, 0, 0); __builtin_amdgcn_s_setprio(0); } while (0)
; #define PG8_WAIT_V(n) asm volatile("s_waitcnt vmcnt(" #n ")" ::: "memory")
; #define PG8_WAIT_L(n) asm volatile("s_waitcnt lgkmcnt(" #n ")" ::: "memory")
; #define PG8_BAR __builtin_amdgcn_s_barrier()
; #define PG8_SCHED __builtin_amdgcn_sched_barrier(0)
; template <class Epi>
; DI void gemm_phase(LAS unsigned char* lds, int tid, const Gemm g, const Order& S, const Epi& E) {
;     ...
;         for (int t = 0; t < nt; t += 2) {
;             const bool last = (t == nt - 2);
;             const char* a1 = cA + (size_t)(t + 1) * kstep;
;             const char* a2 = last ? nA : cA + (size_t)(t + 2) * kstep; const char* b2 = last ? nB : cB + (size_t)(t + 2) * kstep;
;             const char* a3 = a2 + kstep; const char* b3 = b2 + kstep;
;             PG8_LDB(B0, 0, 0); PG8_LDB(B1, 0, 1); PG8_SCHED; PG8_LDA(At, 0, 0); PG8_STAGE(PG8_SA(1, 1), a1 + hstepA, voffA);
;             PG8_WAIT_V(8); PG8_WAIT_L(0); PG8_BAR; PG8_MMA(0, 0, At, B0); PG8_MMA(0, 1, At, B1); PG8_BAR; PG8_SCHED;
;             PG8_LDA(At, 0, 1); PG8_STAGE(PG8_SB(0, 0), b2, voffB); PG8_STAGE(PG8_SB(0, 1), b2 + hstepB, voffB); PG8_STAGE(PG8_SA(0, 0), a2, voffA);
;             PG8_WAIT_V(8); PG8_WAIT_L(0); PG8_BAR; PG8_MMA(1, 0, At, B0); PG8_MMA(1, 1, At, B1); PG8_BAR; PG8_SCHED;
.LBB0_513:
	s_add_u32 s48, s74, 0xfffc0080
	s_addc_u32 s49, s75, -1
	s_add_i32 s51, 0, 0x10000
	s_cmp_eq_u32 s47, 12
	s_cselect_b32 s79, s39, s49
	s_cselect_b32 s78, s40, s48
	s_cselect_b32 s77, s41, s46
	s_cselect_b32 s76, s43, s45
	s_add_i32 s52, 0, 0x14000
	v_add_u32_e32 v156, s51, v145
	v_add_u32_e32 v160, s52, v145
	ds_read_b128 v[140:143], v156
	ds_read_b128 v[148:151], v156 offset:1024
	ds_read_b128 v[152:155], v156 offset:2048
	ds_read_b128 v[156:159], v156 offset:3072
	ds_read_b128 v[164:167], v160
	ds_read_b128 v[170:173], v160 offset:1024
	ds_read_b128 v[174:177], v160 offset:2048
	ds_read_b128 v[196:199], v160 offset:3072
	v_lshl_add_u64 v[160:161], s[74:75], 0, v[136:137]
	s_add_i32 m0, s22, 0xc000
	ds_read_b128 v[200:203], v147
	ds_read_b128 v[204:207], v147 offset:1024
	ds_read_b128 v[208:211], v147 offset:2048
	ds_read_b128 v[212:215], v147 offset:3072
	ds_read_b128 v[216:219], v147 offset:4096
	ds_read_b128 v[220:223], v147 offset:5120
	ds_read_b128 v[224:227], v147 offset:6144
	ds_read_b128 v[228:231], v147 offset:7168
	global_load_lds_dwordx4 v[160:161], off
	v_lshl_add_u64 v[160:161], s[74:75], 0, v[138:139]
	s_add_i32 m0, s22, 0xe000
	s_nop 0
	global_load_lds_dwordx4 v[160:161], off
	s_waitcnt vmcnt(8)
	s_waitcnt lgkmcnt(0)
	s_barrier
	s_setprio 1
	s_waitcnt lgkmcnt(0)
	v_mfma_f32_16x16x32_bf16 v[126:129], v[140:143], v[200:203], v[126:129]
	v_mfma_f32_16x16x32_bf16 v[122:125], v[152:155], v[200:203], v[122:125]
	v_mfma_f32_16x16x32_bf16 v[110:113], v[140:143], v[208:211], v[110:113]
	v_mfma_f32_16x16x32_bf16 v[106:109], v[152:155], v[208:211], v[106:109]
	v_mfma_f32_16x16x32_bf16 v[94:97], v[140:143], v[216:219], v[94:97]
	v_mfma_f32_16x16x32_bf16 v[90:93], v[152:155], v[216:219], v[90:93]
	v_mfma_f32_16x16x32_bf16 v[78:81], v[140:143], v[224:227], v[78:81]
	v_mfma_f32_16x16x32_bf16 v[74:77], v[152:155], v[224:227], v[74:77]
	v_mfma_f32_16x16x32_bf16 v[126:129], v[148:151], v[204:207], v[126:129]
	v_mfma_f32_16x16x32_bf16 v[122:125], v[156:159], v[204:207], v[122:125]
	v_mfma_f32_16x16x32_bf16 v[110:113], v[148:151], v[212:215], v[110:113]
	v_mfma_f32_16x16x32_bf16 v[106:109], v[156:159], v[212:215], v[106:109]
	v_mfma_f32_16x16x32_bf16 v[94:97], v[148:151], v[220:223], v[94:97]
	v_mfma_f32_16x16x32_bf16 v[90:93], v[156:159], v[220:223], v[90:93]
	v_mfma_f32_16x16x32_bf16 v[78:81], v[148:151], v[228:231], v[78:81]
	v_mfma_f32_16x16x32_bf16 v[74:77], v[156:159], v[228:231], v[74:77]
	s_setprio 0
	s_setprio 1
	v_mfma_f32_16x16x32_bf16 v[118:121], v[164:167], v[200:203], v[118:121]
	v_mfma_f32_16x16x32_bf16 v[114:117], v[174:177], v[200:203], v[114:117]
	v_mfma_f32_16x16x32_bf16 v[102:105], v[164:167], v[208:211], v[102:105]
	v_mfma_f32_16x16x32_bf16 v[98:101], v[174:177], v[208:211], v[98:101]
	v_mfma_f32_16x16x32_bf16 v[86:89], v[164:167], v[216:219], v[86:89]
	v_mfma_f32_16x16x32_bf16 v[82:85], v[174:177], v[216:219], v[82:85]
	v_mfma_f32_16x16x32_bf16 v[70:73], v[164:167], v[224:227], v[70:73]
	v_mfma_f32_16x16x32_bf16 v[66:69], v[174:177], v[224:227], v[66:69]
	v_mfma_f32_16x16x32_bf16 v[118:121], v[170:173], v[204:207], v[118:121]
	v_mfma_f32_16x16x32_bf16 v[114:117], v[196:199], v[204:207], v[114:117]
	v_mfma_f32_16x16x32_bf16 v[102:105], v[170:173], v[212:215], v[102:105]
	v_mfma_f32_16x16x32_bf16 v[98:101], v[196:199], v[212:215], v[98:101]
	v_mfma_f32_16x16x32_bf16 v[86:89], v[170:173], v[220:223], v[86:89]
	v_mfma_f32_16x16x32_bf16 v[82:85], v[196:199], v[220:223], v[82:85]
	v_mfma_f32_16x16x32_bf16 v[70:73], v[170:173], v[228:231], v[70:73]
	v_mfma_f32_16x16x32_bf16 v[66:69], v[196:199], v[228:231], v[66:69]
	s_setprio 0
	s_barrier
	s_add_i32 s48, s51, s17
	v_lshl_add_u64 v[160:161], s[76:77], 0, v[0:1]
	s_mov_b32 m0, s48
	ds_read_b128 v[200:203], v147 offset:16384
	ds_read_b128 v[204:207], v147 offset:17408
	ds_read_b128 v[208:211], v147 offset:18432
	ds_read_b128 v[212:215], v147 offset:19456
	ds_read_b128 v[216:219], v147 offset:20480
	ds_read_b128 v[220:223], v147 offset:21504
	ds_read_b128 v[224:227], v147 offset:22528
	ds_read_b128 v[228:231], v147 offset:23552
	global_load_lds_dwordx4 v[160:161], off
	s_add_i32 m0, s48, 0x2000
	s_add_u32 s48, s76, 0x40000
	v_lshl_add_u64 v[178:179], s[76:77], 0, v[134:135]
	s_addc_u32 s49, s77, 0
	s_add_i32 s51, s52, s17
	global_load_lds_dwordx4 v[178:179], off
	v_lshl_add_u64 v[188:189], s[48:49], 0, v[0:1]
	s_mov_b32 m0, s51
	v_lshl_add_u64 v[190:191], s[78:79], 0, v[132:133]
	global_load_lds_dwordx4 v[188:189], off
	v_lshl_add_u64 v[188:189], s[48:49], 0, v[134:135]
	s_add_i32 m0, s51, 0x2000
	s_nop 0
	global_load_lds_dwordx4 v[188:189], off
	v_lshl_add_u64 v[188:189], s[78:79], 0, v[130:131]
	s_mov_b32 m0, s22
	s_nop 0
	global_load_lds_dwordx4 v[188:189], off
	s_mov_b32 m0, s26
	s_nop 0
	global_load_lds_dwordx4 v[190:191], off
	s_waitcnt vmcnt(8)
	s_waitcnt lgkmcnt(0)
	s_barrier
; #define PG8_STAGE(bufoff, gbase, voff) do { _Pragma("unroll") for (int _i = 0; _i < 2; ++_i) \
;         __builtin_amdgcn_global_load_lds((const unsigned*)((const char*)(gbase) + (voff)[_i]), (LAS unsigned*)(lds + (bufoff) + ldsw + _i * 8192), 16, 0, 0); } while (0)
; #define PG8_LDA(dst, b, h) do { _Pragma("unroll") for (int m = 0; m < 4; ++m) _Pragma("unroll") for (int k = 0; k < 2; ++k) dst[m][k] = *(const LAS bf16x8*)(lds + PG8_SA(b, h) + aoff + m * 2048 + k * 1024); } while (0)
; #define PG8_LDB(dst, b, h) do { _Pragma("unroll") for (int n = 0; n < 2; ++n) _Pragma("unroll") for (int k = 0; k < 2; ++k) dst[n][k] = *(const LAS bf16x8*)(lds + PG8_SB(b, h) + boff + n * 2048 + k * 1024); } while (0)
; #define PG8_MMA(ai, bj, At, Bt) do { __builtin_amdgcn_s_setprio(1); _Pragma("unroll") for (int m = 0; m < 4; ++m) _Pragma("unroll") for (int n = 0; n < 2; ++n) _Pragma("unroll") for (int k = 0; k < 2; ++k) \
;         acc[ai][bj][m][n] = __builtin_amdgcn_mfma_f32_16x16x32_bf16(Bt[n][k], At[m][k], acc[ai][bj][m][n], 0, 0, 0); __builtin_amdgcn_s_setprio(0); } while (0)
; #define PG8_WAIT_V(n) asm volatile("s_waitcnt vmcnt(" #n ")" ::: "memory")
; #define PG8_WAIT_L(n) asm volatile("s_waitcnt lgkmcnt(" #n ")" ::: "memory")
; #define PG8_BAR __builtin_amdgcn_s_barrier()
; #define PG8_SCHED __builtin_amdgcn_sched_barrier(0)
; template <class Epi>
; DI void gemm_phase(LAS unsigned char* lds, int tid, const Gemm g, const Order& S, const Epi& E) {
;     ...
;             PG8_WAIT_V(8); PG8_WAIT_L(0); PG8_BAR; PG8_MMA(1, 0, At, B0); PG8_MMA(1, 1, At, B1); PG8_BAR; PG8_SCHED;
;             PG8_LDB(B0, 1, 0); PG8_LDB(B1, 1, 1); PG8_SCHED; PG8_LDA(At, 1, 0); PG8_STAGE(PG8_SA(0, 1), a2 + hstepA, voffA);
;             PG8_WAIT_V(8); PG8_WAIT_L(0); PG8_BAR; PG8_MMA(0, 0, At, B0); PG8_MMA(0, 1, At, B1); PG8_BAR; PG8_SCHED;
	s_setprio 1
	s_waitcnt lgkmcnt(0)
	v_mfma_f32_16x16x32_bf16 v[62:65], v[140:143], v[200:203], v[62:65]
	v_mfma_f32_16x16x32_bf16 v[58:61], v[152:155], v[200:203], v[58:61]
	v_mfma_f32_16x16x32_bf16 v[46:49], v[140:143], v[208:211], v[46:49]
	v_mfma_f32_16x16x32_bf16 v[42:45], v[152:155], v[208:211], v[42:45]
	v_mfma_f32_16x16x32_bf16 v[30:33], v[140:143], v[216:219], v[30:33]
	v_mfma_f32_16x16x32_bf16 v[26:29], v[152:155], v[216:219], v[26:29]
	v_mfma_f32_16x16x32_bf16 v[14:17], v[140:143], v[224:227], v[14:17]
	v_mfma_f32_16x16x32_bf16 v[10:13], v[152:155], v[224:227], v[10:13]
	v_mfma_f32_16x16x32_bf16 v[62:65], v[148:151], v[204:207], v[62:65]
	v_mfma_f32_16x16x32_bf16 v[58:61], v[156:159], v[204:207], v[58:61]
	v_mfma_f32_16x16x32_bf16 v[46:49], v[148:151], v[212:215], v[46:49]
	v_mfma_f32_16x16x32_bf16 v[42:45], v[156:159], v[212:215], v[42:45]
	v_mfma_f32_16x16x32_bf16 v[30:33], v[148:151], v[220:223], v[30:33]
	v_mfma_f32_16x16x32_bf16 v[26:29], v[156:159], v[220:223], v[26:29]
	v_mfma_f32_16x16x32_bf16 v[14:17], v[148:151], v[228:231], v[14:17]
	v_mfma_f32_16x16x32_bf16 v[10:13], v[156:159], v[228:231], v[10:13]
	s_setprio 0
	s_setprio 1
	v_mfma_f32_16x16x32_bf16 v[54:57], v[164:167], v[200:203], v[54:57]
	v_mfma_f32_16x16x32_bf16 v[50:53], v[174:177], v[200:203], v[50:53]
	v_mfma_f32_16x16x32_bf16 v[38:41], v[164:167], v[208:211], v[38:41]
	v_mfma_f32_16x16x32_bf16 v[34:37], v[174:177], v[208:211], v[34:37]
	v_mfma_f32_16x16x32_bf16 v[22:25], v[164:167], v[216:219], v[22:25]
	v_mfma_f32_16x16x32_bf16 v[18:21], v[174:177], v[216:219], v[18:21]
	v_mfma_f32_16x16x32_bf16 v[6:9], v[164:167], v[224:227], v[6:9]
	v_mfma_f32_16x16x32_bf16 v[2:5], v[174:177], v[224:227], v[2:5]
	v_mfma_f32_16x16x32_bf16 v[54:57], v[170:173], v[204:207], v[54:57]
	v_mfma_f32_16x16x32_bf16 v[50:53], v[196:199], v[204:207], v[50:53]
	v_mfma_f32_16x16x32_bf16 v[38:41], v[170:173], v[212:215], v[38:41]
	v_mfma_f32_16x16x32_bf16 v[34:37], v[196:199], v[212:215], v[34:37]
	v_mfma_f32_16x16x32_bf16 v[22:25], v[170:173], v[220:223], v[22:25]
	v_mfma_f32_16x16x32_bf16 v[18:21], v[196:199], v[220:223], v[18:21]
	v_mfma_f32_16x16x32_bf16 v[6:9], v[170:173], v[228:231], v[6:9]
	v_mfma_f32_16x16x32_bf16 v[2:5], v[196:199], v[228:231], v[2:5]
	s_setprio 0
	s_barrier
	s_add_i32 s51, 0, 0x18000
	s_add_i32 s52, 0, 0x1c000
	v_add_u32_e32 v156, s51, v145
	v_add_u32_e32 v168, s52, v145
	ds_read_b128 v[140:143], v156
	ds_read_b128 v[148:151], v156 offset:1024
	ds_read_b128 v[152:155], v156 offset:2048
	ds_read_b128 v[156:159], v156 offset:3072
	ds_read_b128 v[164:167], v168
	ds_read_b128 v[170:173], v168 offset:1024
	ds_read_b128 v[174:177], v168 offset:2048
	ds_read_b128 v[196:199], v168 offset:3072
	s_add_u32 s48, s78, 0x40000
	s_addc_u32 s49, s79, 0
	s_mov_b32 m0, s28
	v_lshl_add_u64 v[232:233], s[48:49], 0, v[130:131]
	ds_read_b128 v[200:203], v147 offset:32768
	ds_read_b128 v[204:207], v147 offset:33792
	ds_read_b128 v[208:211], v147 offset:34816
	ds_read_b128 v[212:215], v147 offset:35840
	ds_read_b128 v[216:219], v147 offset:36864
	ds_read_b128 v[220:223], v147 offset:37888
	ds_read_b128 v[224:227], v147 offset:38912
	ds_read_b128 v[228:231], v147 offset:39936
	global_load_lds_dwordx4 v[232:233], off
	v_lshl_add_u64 v[232:233], s[48:49], 0, v[132:133]
	s_mov_b32 m0, s30
	s_nop 0
	global_load_lds_dwordx4 v[232:233], off
	s_waitcnt vmcnt(8)
	s_waitcnt lgkmcnt(0)
	s_barrier
	s_setprio 1
	s_waitcnt lgkmcnt(0)
	v_mfma_f32_16x16x32_bf16 v[126:129], v[140:143], v[200:203], v[126:129]
	v_mfma_f32_16x16x32_bf16 v[122:125], v[152:155], v[200:203], v[122:125]
	v_mfma_f32_16x16x32_bf16 v[110:113], v[140:143], v[208:211], v[110:113]
	v_mfma_f32_16x16x32_bf16 v[106:109], v[152:155], v[208:211], v[106:109]
	v_mfma_f32_16x16x32_bf16 v[94:97], v[140:143], v[216:219], v[94:97]
	v_mfma_f32_16x16x32_bf16 v[90:93], v[152:155], v[216:219], v[90:93]
	v_mfma_f32_16x16x32_bf16 v[78:81], v[140:143], v[224:227], v[78:81]
	v_mfma_f32_16x16x32_bf16 v[74:77], v[152:155], v[224:227], v[74:77]
	v_mfma_f32_16x16x32_bf16 v[126:129], v[148:151], v[204:207], v[126:129]
	v_mfma_f32_16x16x32_bf16 v[122:125], v[156:159], v[204:207], v[122:125]
	v_mfma_f32_16x16x32_bf16 v[110:113], v[148:151], v[212:215], v[110:113]
	v_mfma_f32_16x16x32_bf16 v[106:109], v[156:159], v[212:215], v[106:109]
	v_mfma_f32_16x16x32_bf16 v[94:97], v[148:151], v[220:223], v[94:97]
	v_mfma_f32_16x16x32_bf16 v[90:93], v[156:159], v[220:223], v[90:93]
	v_mfma_f32_16x16x32_bf16 v[78:81], v[148:151], v[228:231], v[78:81]
	v_mfma_f32_16x16x32_bf16 v[74:77], v[156:159], v[228:231], v[74:77]
	s_setprio 0
	s_setprio 1
	v_mfma_f32_16x16x32_bf16 v[118:121], v[164:167], v[200:203], v[118:121]
	v_mfma_f32_16x16x32_bf16 v[114:117], v[174:177], v[200:203], v[114:117]
	v_mfma_f32_16x16x32_bf16 v[102:105], v[164:167], v[208:211], v[102:105]
	v_mfma_f32_16x16x32_bf16 v[98:101], v[174:177], v[208:211], v[98:101]
	v_mfma_f32_16x16x32_bf16 v[86:89], v[164:167], v[216:219], v[86:89]
	v_mfma_f32_16x16x32_bf16 v[82:85], v[174:177], v[216:219], v[82:85]
	v_mfma_f32_16x16x32_bf16 v[70:73], v[164:167], v[224:227], v[70:73]
	v_mfma_f32_16x16x32_bf16 v[66:69], v[174:177], v[224:227], v[66:69]
	v_mfma_f32_16x16x32_bf16 v[118:121], v[170:173], v[204:207], v[118:121]
	v_mfma_f32_16x16x32_bf16 v[114:117], v[196:199], v[204:207], v[114:117]
	v_mfma_f32_16x16x32_bf16 v[102:105], v[170:173], v[212:215], v[102:105]
	v_mfma_f32_16x16x32_bf16 v[98:101], v[196:199], v[212:215], v[98:101]
	v_mfma_f32_16x16x32_bf16 v[86:89], v[170:173], v[220:223], v[86:89]
	v_mfma_f32_16x16x32_bf16 v[82:85], v[196:199], v[220:223], v[82:85]
	v_mfma_f32_16x16x32_bf16 v[70:73], v[170:173], v[228:231], v[70:73]
	v_mfma_f32_16x16x32_bf16 v[66:69], v[196:199], v[228:231], v[66:69]
	s_setprio 0
	s_barrier
; DI unsigned pk2(float lo, float hi) { f32x2 v = {lo, hi}; bf16x2_t b = __builtin_convertvector(v, bf16x2_t); return __builtin_bit_cast(unsigned, b); }
; #define PG8_STAGE(bufoff, gbase, voff) do { _Pragma("unroll") for (int _i = 0; _i < 2; ++_i) \
;         __builtin_amdgcn_global_load_lds((const unsigned*)((const char*)(gbase) + (voff)[_i]), (LAS unsigned*)(lds + (bufoff) + ldsw + _i * 8192), 16, 0, 0); } while (0)
; #define PG8_LDA(dst, b, h) do { _Pragma("unroll") for (int m = 0; m < 4; ++m) _Pragma("unroll") for (int k = 0; k < 2; ++k) dst[m][k] = *(const LAS bf16x8*)(lds + PG8_SA(b, h) + aoff + m * 2048 + k * 1024); } while (0)
; #define PG8_WAIT_V(n) asm volatile("s_waitcnt vmcnt(" #n ")" ::: "memory")
; template <class Epi>
; DI void gemm_phase(LAS unsigned char* lds, int tid, const Gemm g, const Order& S, const Epi& E) {
;     ...
;             PG8_LDA(At, 1, 1); PG8_STAGE(PG8_SB(1, 0), b3, voffB); PG8_STAGE(PG8_SB(1, 1), b3 + hstepB, voffB); PG8_STAGE(PG8_SA(1, 0), a3, voffA);
;             PG8_WAIT_V(8); PG8_WAIT_L(0); PG8_BAR; PG8_MMA(1, 0, At, B0); PG8_MMA(1, 1, At, B1); PG8_BAR; PG8_SCHED;
;         }
;         if (wr == 0) PG8_BAR;
;         E(acc, cur, wr, wc, fr, fq);
;     DI void operator()(const f32x4 (&acc)[2][2][4][2], const Unit& u, int wr, int wc, int fr, int fq) const {
;         const int row0 = u.pm * BM + wr * 64 + fr, col0 = u.pn * 128 + wc * 32 + 8 * fq;
; #pragma unroll
;         for (int ai = 0; ai < 2; ++ai)
; #pragma unroll
;             for (int m = 0; m < 4; ++m) {
;                 bf16_t* rowp = O + (size_t)(row0 + ai * HALF + m * 16) * DFF + col0;
;                 const f32x4 g0 = acc[ai][0][m][0], g1 = acc[ai][0][m][1], u0 = acc[ai][1][m][0], u1 = acc[ai][1][m][1];
;                 u32x4 w;
;                 f32x4 e0, e1;
; #pragma unroll
;                 for (int e = 0; e < 4; ++e) { e0[e] = __builtin_amdgcn_exp2f(-g0[e]); e1[e] = __builtin_amdgcn_exp2f(-g1[e]); }
;                 e0 = e0 + 1.0f; e1 = e1 + 1.0f;
; #pragma unroll
;                 for (int e = 0; e < 4; ++e) { e0[e] = __builtin_amdgcn_rcpf(e0[e]); e1[e] = __builtin_amdgcn_rcpf(e1[e]); }
;                 const f32x4 r0 = g0 * u0 * e0, r1 = g1 * u1 * e1;
;                 w.x = pk2(r0[0], r0[1]); w.y = pk2(r0[2], r0[3]); w.z = pk2(r1[0], r1[1]); w.w = pk2(r1[2], r1[3]);
;                 __builtin_nontemporal_store(w, (u32x4*)rowp);
	s_add_i32 s48, s51, s17
	v_lshl_add_u64 v[160:161], v[160:161], 0, s[24:25]
	s_mov_b32 m0, s48
	ds_read_b128 v[200:203], v147 offset:49152
	ds_read_b128 v[204:207], v147 offset:50176
	ds_read_b128 v[208:211], v147 offset:51200
	ds_read_b128 v[212:215], v147 offset:52224
	ds_read_b128 v[216:219], v147 offset:53248
	ds_read_b128 v[220:223], v147 offset:54272
	ds_read_b128 v[224:227], v147 offset:55296
	ds_read_b128 v[228:231], v147 offset:56320
	global_load_lds_dwordx4 v[160:161], off
	s_add_i32 m0, s48, 0x2000
	s_add_u32 s48, s76, 0x40080
	v_lshl_add_u64 v[160:161], v[178:179], 0, s[24:25]
	s_addc_u32 s49, s77, 0
	s_add_i32 s51, s52, s17
	global_load_lds_dwordx4 v[160:161], off
	v_lshl_add_u64 v[160:161], s[48:49], 0, v[0:1]
	s_mov_b32 m0, s51
	s_nop 0
	global_load_lds_dwordx4 v[160:161], off
	v_lshl_add_u64 v[160:161], s[48:49], 0, v[134:135]
	s_add_i32 m0, s51, 0x2000
	s_nop 0
	global_load_lds_dwordx4 v[160:161], off
	v_lshl_add_u64 v[160:161], v[188:189], 0, s[24:25]
	s_mov_b32 m0, s34
	s_nop 0
	global_load_lds_dwordx4 v[160:161], off
	v_lshl_add_u64 v[160:161], v[190:191], 0, s[24:25]
	s_mov_b32 m0, s36
	s_nop 0
	global_load_lds_dwordx4 v[160:161], off
	s_waitcnt vmcnt(8)
	s_waitcnt lgkmcnt(0)
	s_barrier
	s_setprio 1
	s_waitcnt lgkmcnt(0)
	v_mfma_f32_16x16x32_bf16 v[62:65], v[140:143], v[200:203], v[62:65]
	v_mfma_f32_16x16x32_bf16 v[58:61], v[152:155], v[200:203], v[58:61]
	v_mfma_f32_16x16x32_bf16 v[46:49], v[140:143], v[208:211], v[46:49]
	v_mfma_f32_16x16x32_bf16 v[42:45], v[152:155], v[208:211], v[42:45]
	v_mfma_f32_16x16x32_bf16 v[30:33], v[140:143], v[216:219], v[30:33]
	v_mfma_f32_16x16x32_bf16 v[26:29], v[152:155], v[216:219], v[26:29]
	v_mfma_f32_16x16x32_bf16 v[14:17], v[140:143], v[224:227], v[14:17]
	v_mfma_f32_16x16x32_bf16 v[10:13], v[152:155], v[224:227], v[10:13]
	v_mfma_f32_16x16x32_bf16 v[62:65], v[148:151], v[204:207], v[62:65]
	v_mfma_f32_16x16x32_bf16 v[58:61], v[156:159], v[204:207], v[58:61]
	v_mfma_f32_16x16x32_bf16 v[46:49], v[148:151], v[212:215], v[46:49]
	v_mfma_f32_16x16x32_bf16 v[42:45], v[156:159], v[212:215], v[42:45]
	v_mfma_f32_16x16x32_bf16 v[30:33], v[148:151], v[220:223], v[30:33]
	v_mfma_f32_16x16x32_bf16 v[26:29], v[156:159], v[220:223], v[26:29]
	v_mfma_f32_16x16x32_bf16 v[14:17], v[148:151], v[228:231], v[14:17]
	v_mfma_f32_16x16x32_bf16 v[10:13], v[156:159], v[228:231], v[10:13]
	s_setprio 0
	s_setprio 1
	v_mfma_f32_16x16x32_bf16 v[54:57], v[164:167], v[200:203], v[54:57]
	v_mfma_f32_16x16x32_bf16 v[50:53], v[174:177], v[200:203], v[50:53]
	v_mfma_f32_16x16x32_bf16 v[38:41], v[164:167], v[208:211], v[38:41]
	v_mfma_f32_16x16x32_bf16 v[34:37], v[174:177], v[208:211], v[34:37]
	v_mfma_f32_16x16x32_bf16 v[22:25], v[164:167], v[216:219], v[22:25]
	v_mfma_f32_16x16x32_bf16 v[18:21], v[174:177], v[216:219], v[18:21]
	v_mfma_f32_16x16x32_bf16 v[6:9], v[164:167], v[224:227], v[6:9]
	v_mfma_f32_16x16x32_bf16 v[2:5], v[174:177], v[224:227], v[2:5]
	v_mfma_f32_16x16x32_bf16 v[54:57], v[170:173], v[204:207], v[54:57]
	v_mfma_f32_16x16x32_bf16 v[50:53], v[196:199], v[204:207], v[50:53]
	v_mfma_f32_16x16x32_bf16 v[38:41], v[170:173], v[212:215], v[38:41]
	v_mfma_f32_16x16x32_bf16 v[34:37], v[196:199], v[212:215], v[34:37]
	v_mfma_f32_16x16x32_bf16 v[22:25], v[170:173], v[220:223], v[22:25]
	v_mfma_f32_16x16x32_bf16 v[18:21], v[196:199], v[220:223], v[18:21]
	v_mfma_f32_16x16x32_bf16 v[6:9], v[170:173], v[228:231], v[6:9]
	v_mfma_f32_16x16x32_bf16 v[2:5], v[196:199], v[228:231], v[2:5]
	s_setprio 0
	s_barrier
	s_add_i32 s47, s47, 2
	s_add_u32 s74, s74, 0x100
	s_addc_u32 s75, s75, 0
	s_add_u32 s45, s45, 0x100
	s_addc_u32 s46, s46, 0
	s_cmp_gt_u32 s47, 13
	s_cbranch_scc0 .LBB0_513
	s_andn2_b64 vcc, s[8:9], s[4:5]
	s_and_b64 vcc, exec, vcc
	s_cbranch_vccz .LBB0_516
	s_barrier
.LBB0_516:
	v_exp_f32_e64 v150, -v126
	v_exp_f32_e64 v152, -v122
	v_exp_f32_e64 v151, -v127
	v_exp_f32_e64 v154, -v128
	v_exp_f32_e64 v155, -v129
	v_exp_f32_e64 v156, -v124
	v_exp_f32_e64 v157, -v125
	v_exp_f32_e64 v153, -v123
	v_pk_add_f32 v[154:155], v[154:155], 1.0 op_sel_hi:[1,0]
	v_pk_add_f32 v[150:151], v[150:151], 1.0 op_sel_hi:[1,0]
	v_pk_add_f32 v[156:157], v[156:157], 1.0 op_sel_hi:[1,0]
	v_pk_add_f32 v[152:153], v[152:153], 1.0 op_sel_hi:[1,0]
	v_rcp_f32_e32 v150, v150
	v_rcp_f32_e32 v152, v152
	v_rcp_f32_e32 v151, v151
	v_rcp_f32_e32 v153, v153
	v_rcp_f32_e32 v154, v154
	v_rcp_f32_e32 v156, v156
	v_rcp_f32_e32 v155, v155
	v_rcp_f32_e32 v157, v157
	v_lshl_or_b32 v142, s33, 7, v146
	v_lshl_add_u32 v158, s72, 8, v144
	v_ashrrev_i32_e32 v143, 31, v142
	v_mov_b64_e32 v[140:141], s[62:63]
	v_pk_mul_f32 v[120:121], v[128:129], v[120:121]
	v_pk_mul_f32 v[118:119], v[126:127], v[118:119]
	v_pk_mul_f32 v[116:117], v[124:125], v[116:117]
	v_pk_mul_f32 v[114:115], v[122:123], v[114:115]
	v_mad_i64_i32 v[148:149], s[40:41], v158, s38, v[140:141]
	v_lshlrev_b64 v[142:143], 1, v[142:143]
	v_pk_mul_f32 v[120:121], v[154:155], v[120:121]
	v_pk_mul_f32 v[118:119], v[150:151], v[118:119]
	v_pk_mul_f32 v[122:123], v[156:157], v[116:117]
	v_pk_mul_f32 v[116:117], v[152:153], v[114:115]
	v_lshl_add_u64 v[148:149], v[148:149], 0, v[142:143]
	v_cvt_pk_bf16_f32 v114, v118, v119
	v_cvt_pk_bf16_f32 v115, v120, v121
	v_cvt_pk_bf16_f32 v116, v116, v117
	v_cvt_pk_bf16_f32 v117, v122, v123
	global_store_dwordx4 v[148:149], v[114:117], off nt
	v_exp_f32_e64 v118, -v106
	v_exp_f32_e64 v120, -v112
	v_exp_f32_e64 v116, -v110
	v_exp_f32_e64 v117, -v111
	v_exp_f32_e64 v121, -v113
	v_exp_f32_e64 v122, -v108
	v_exp_f32_e64 v123, -v109
	v_exp_f32_e64 v119, -v107
	v_pk_add_f32 v[120:121], v[120:121], 1.0 op_sel_hi:[1,0]
	v_pk_add_f32 v[116:117], v[116:117], 1.0 op_sel_hi:[1,0]
; DI unsigned pk2(float lo, float hi) { f32x2 v = {lo, hi}; bf16x2_t b = __builtin_convertvector(v, bf16x2_t); return __builtin_bit_cast(unsigned, b); }
;     DI void operator()(const f32x4 (&acc)[2][2][4][2], const Unit& u, int wr, int wc, int fr, int fq) const {
;         const int row0 = u.pm * BM + wr * 64 + fr, col0 = u.pn * 128 + wc * 32 + 8 * fq;
; #pragma unroll
;         for (int ai = 0; ai < 2; ++ai)
; #pragma unroll
;             for (int m = 0; m < 4; ++m) {
;                 bf16_t* rowp = O + (size_t)(row0 + ai * HALF + m * 16) * DFF + col0;
;                 const f32x4 g0 = acc[ai][0][m][0], g1 = acc[ai][0][m][1], u0 = acc[ai][1][m][0], u1 = acc[ai][1][m][1];
;                 u32x4 w;
;                 f32x4 e0, e1;
; #pragma unroll
;                 for (int e = 0; e < 4; ++e) { e0[e] = __builtin_amdgcn_exp2f(-g0[e]); e1[e] = __builtin_amdgcn_exp2f(-g1[e]); }
;                 e0 = e0 + 1.0f; e1 = e1 + 1.0f;
; #pragma unroll
;                 for (int e = 0; e < 4; ++e) { e0[e] = __builtin_amdgcn_rcpf(e0[e]); e1[e] = __builtin_amdgcn_rcpf(e1[e]); }
;                 const f32x4 r0 = g0 * u0 * e0, r1 = g1 * u1 * e1;
;                 w.x = pk2(r0[0], r0[1]); w.y = pk2(r0[2], r0[3]); w.z = pk2(r1[0], r1[1]); w.w = pk2(r1[2], r1[3]);
;                 __builtin_nontemporal_store(w, (u32x4*)rowp);
;             }
	v_pk_add_f32 v[122:123], v[122:123], 1.0 op_sel_hi:[1,0]
	v_pk_add_f32 v[118:119], v[118:119], 1.0 op_sel_hi:[1,0]
	v_rcp_f32_e32 v116, v116
	v_rcp_f32_e32 v118, v118
	v_rcp_f32_e32 v117, v117
	v_rcp_f32_e32 v119, v119
	v_rcp_f32_e32 v120, v120
	v_rcp_f32_e32 v122, v122
	v_rcp_f32_e32 v121, v121
	v_rcp_f32_e32 v123, v123
	v_or_b32_e32 v114, 16, v158
	v_pk_mul_f32 v[104:105], v[112:113], v[104:105]
	v_pk_mul_f32 v[102:103], v[110:111], v[102:103]
	v_pk_mul_f32 v[100:101], v[108:109], v[100:101]
	v_pk_mul_f32 v[98:99], v[106:107], v[98:99]
	v_mad_i64_i32 v[114:115], s[40:41], v114, s38, v[140:141]
	v_pk_mul_f32 v[104:105], v[120:121], v[104:105]
	v_pk_mul_f32 v[102:103], v[116:117], v[102:103]
	v_pk_mul_f32 v[106:107], v[122:123], v[100:101]
	v_pk_mul_f32 v[100:101], v[118:119], v[98:99]
	v_lshl_add_u64 v[114:115], v[114:115], 0, v[142:143]
	v_cvt_pk_bf16_f32 v98, v102, v103
	v_cvt_pk_bf16_f32 v99, v104, v105
	v_cvt_pk_bf16_f32 v100, v100, v101
	v_cvt_pk_bf16_f32 v101, v106, v107
	global_store_dwordx4 v[114:115], v[98:101], off nt
	v_exp_f32_e64 v102, -v90
	v_exp_f32_e64 v104, -v96
	v_exp_f32_e64 v100, -v94
	v_exp_f32_e64 v101, -v95
	v_exp_f32_e64 v105, -v97
	v_exp_f32_e64 v106, -v92
	v_exp_f32_e64 v107, -v93
	v_exp_f32_e64 v103, -v91
	v_pk_add_f32 v[104:105], v[104:105], 1.0 op_sel_hi:[1,0]
	v_pk_add_f32 v[100:101], v[100:101], 1.0 op_sel_hi:[1,0]
	v_pk_add_f32 v[106:107], v[106:107], 1.0 op_sel_hi:[1,0]
	v_pk_add_f32 v[102:103], v[102:103], 1.0 op_sel_hi:[1,0]
	v_rcp_f32_e32 v100, v100
	v_rcp_f32_e32 v102, v102
	v_rcp_f32_e32 v101, v101
	v_rcp_f32_e32 v103, v103
	v_rcp_f32_e32 v104, v104
	v_rcp_f32_e32 v106, v106
	v_rcp_f32_e32 v105, v105
	v_rcp_f32_e32 v107, v107
	v_or_b32_e32 v98, 32, v158
	v_pk_mul_f32 v[88:89], v[96:97], v[88:89]
	v_pk_mul_f32 v[86:87], v[94:95], v[86:87]
	v_pk_mul_f32 v[84:85], v[92:93], v[84:85]
	v_pk_mul_f32 v[82:83], v[90:91], v[82:83]
	v_mad_i64_i32 v[98:99], s[40:41], v98, s38, v[140:141]
	v_pk_mul_f32 v[88:89], v[104:105], v[88:89]
	v_pk_mul_f32 v[86:87], v[100:101], v[86:87]
	v_pk_mul_f32 v[90:91], v[106:107], v[84:85]
	v_pk_mul_f32 v[84:85], v[102:103], v[82:83]
	v_lshl_add_u64 v[98:99], v[98:99], 0, v[142:143]
	v_cvt_pk_bf16_f32 v82, v86, v87
	v_cvt_pk_bf16_f32 v83, v88, v89
	v_cvt_pk_bf16_f32 v84, v84, v85
	v_cvt_pk_bf16_f32 v85, v90, v91
	global_store_dwordx4 v[98:99], v[82:85], off nt
	v_exp_f32_e64 v86, -v74
	v_exp_f32_e64 v88, -v80
	v_exp_f32_e64 v84, -v78
	v_exp_f32_e64 v85, -v79
	v_exp_f32_e64 v89, -v81
	v_exp_f32_e64 v90, -v76
	v_exp_f32_e64 v91, -v77
	v_exp_f32_e64 v87, -v75
	v_pk_add_f32 v[88:89], v[88:89], 1.0 op_sel_hi:[1,0]
	v_pk_add_f32 v[84:85], v[84:85], 1.0 op_sel_hi:[1,0]
	v_pk_add_f32 v[90:91], v[90:91], 1.0 op_sel_hi:[1,0]
	v_pk_add_f32 v[86:87], v[86:87], 1.0 op_sel_hi:[1,0]
	v_rcp_f32_e32 v84, v84
	v_rcp_f32_e32 v86, v86
	v_rcp_f32_e32 v85, v85
	v_rcp_f32_e32 v87, v87
	v_rcp_f32_e32 v88, v88
	v_rcp_f32_e32 v90, v90
	v_rcp_f32_e32 v89, v89
	v_rcp_f32_e32 v91, v91
	v_or_b32_e32 v82, 48, v158
	v_pk_mul_f32 v[72:73], v[80:81], v[72:73]
	v_pk_mul_f32 v[70:71], v[78:79], v[70:71]
	v_pk_mul_f32 v[68:69], v[76:77], v[68:69]
	v_pk_mul_f32 v[66:67], v[74:75], v[66:67]
	v_mad_i64_i32 v[82:83], s[40:41], v82, s38, v[140:141]
	v_pk_mul_f32 v[72:73], v[88:89], v[72:73]
	v_pk_mul_f32 v[70:71], v[84:85], v[70:71]
	v_pk_mul_f32 v[74:75], v[90:91], v[68:69]
	v_pk_mul_f32 v[68:69], v[86:87], v[66:67]
	v_lshl_add_u64 v[82:83], v[82:83], 0, v[142:143]
	v_cvt_pk_bf16_f32 v66, v70, v71
	v_cvt_pk_bf16_f32 v67, v72, v73
	v_cvt_pk_bf16_f32 v68, v68, v69
	v_cvt_pk_bf16_f32 v69, v74, v75
	global_store_dwordx4 v[82:83], v[66:69], off nt
	v_exp_f32_e64 v70, -v58
	v_exp_f32_e64 v72, -v64
	v_exp_f32_e64 v68, -v62
	v_exp_f32_e64 v69, -v63
	v_exp_f32_e64 v73, -v65
	v_exp_f32_e64 v74, -v60
	v_exp_f32_e64 v75, -v61
	v_exp_f32_e64 v71, -v59
	v_pk_add_f32 v[72:73], v[72:73], 1.0 op_sel_hi:[1,0]
	v_pk_add_f32 v[68:69], v[68:69], 1.0 op_sel_hi:[1,0]
	v_pk_add_f32 v[74:75], v[74:75], 1.0 op_sel_hi:[1,0]
	v_pk_add_f32 v[70:71], v[70:71], 1.0 op_sel_hi:[1,0]
	v_rcp_f32_e32 v68, v68
	v_rcp_f32_e32 v70, v70
	v_rcp_f32_e32 v69, v69
	v_rcp_f32_e32 v71, v71
	v_rcp_f32_e32 v72, v72
	v_rcp_f32_e32 v74, v74
	v_rcp_f32_e32 v73, v73
	v_rcp_f32_e32 v75, v75
	v_add_u32_e32 v66, 0x80, v158
	v_pk_mul_f32 v[56:57], v[64:65], v[56:57]
	v_pk_mul_f32 v[54:55], v[62:63], v[54:55]
	v_pk_mul_f32 v[52:53], v[60:61], v[52:53]
; DI unsigned pk2(float lo, float hi) { f32x2 v = {lo, hi}; bf16x2_t b = __builtin_convertvector(v, bf16x2_t); return __builtin_bit_cast(unsigned, b); }
; #define PG8_BAR __builtin_amdgcn_s_barrier()
; template <class Epi>
; DI void gemm_phase(LAS unsigned char* lds, int tid, const Gemm g, const Order& S, const Epi& E) {
;     ...
;         if (wr == 0) PG8_BAR;
;         E(acc, cur, wr, wc, fr, fq);
;         if (!has_next) break;
; #pragma unroll
;         for (int a = 0; a < 2; ++a)
; #pragma unroll
;             for (int b = 0; b < 2; ++b)
; #pragma unroll
;                 for (int m = 0; m < 4; ++m)
; #pragma unroll
;                     for (int n = 0; n < 2; ++n) acc[a][b][m][n] = (f32x4){0.f, 0.f, 0.f, 0.f};
;         cur = nxt; cA = nA; cB = nB; ++ui;
;         if (wr == 1) PG8_BAR;
;     }
;     DI void operator()(const f32x4 (&acc)[2][2][4][2], const Unit& u, int wr, int wc, int fr, int fq) const {
;     ...
;             for (int m = 0; m < 4; ++m) {
;                 bf16_t* rowp = O + (size_t)(row0 + ai * HALF + m * 16) * DFF + col0;
;                 const f32x4 g0 = acc[ai][0][m][0], g1 = acc[ai][0][m][1], u0 = acc[ai][1][m][0], u1 = acc[ai][1][m][1];
;                 u32x4 w;
;                 f32x4 e0, e1;
; #pragma unroll
;                 for (int e = 0; e < 4; ++e) { e0[e] = __builtin_amdgcn_exp2f(-g0[e]); e1[e] = __builtin_amdgcn_exp2f(-g1[e]); }
;                 e0 = e0 + 1.0f; e1 = e1 + 1.0f;
; #pragma unroll
;                 for (int e = 0; e < 4; ++e) { e0[e] = __builtin_amdgcn_rcpf(e0[e]); e1[e] = __builtin_amdgcn_rcpf(e1[e]); }
;                 const f32x4 r0 = g0 * u0 * e0, r1 = g1 * u1 * e1;
;                 w.x = pk2(r0[0], r0[1]); w.y = pk2(r0[2], r0[3]); w.z = pk2(r1[0], r1[1]); w.w = pk2(r1[2], r1[3]);
;                 __builtin_nontemporal_store(w, (u32x4*)rowp);
;             }
	v_pk_mul_f32 v[50:51], v[58:59], v[50:51]
	v_mad_i64_i32 v[66:67], s[40:41], v66, s38, v[140:141]
	v_pk_mul_f32 v[56:57], v[72:73], v[56:57]
	v_pk_mul_f32 v[54:55], v[68:69], v[54:55]
	v_pk_mul_f32 v[58:59], v[74:75], v[52:53]
	v_pk_mul_f32 v[52:53], v[70:71], v[50:51]
	v_lshl_add_u64 v[66:67], v[66:67], 0, v[142:143]
	v_cvt_pk_bf16_f32 v50, v54, v55
	v_cvt_pk_bf16_f32 v51, v56, v57
	v_cvt_pk_bf16_f32 v52, v52, v53
	v_cvt_pk_bf16_f32 v53, v58, v59
	global_store_dwordx4 v[66:67], v[50:53], off nt
	v_exp_f32_e64 v54, -v42
	v_exp_f32_e64 v56, -v48
	v_exp_f32_e64 v52, -v46
	v_exp_f32_e64 v53, -v47
	v_exp_f32_e64 v57, -v49
	v_exp_f32_e64 v58, -v44
	v_exp_f32_e64 v59, -v45
	v_exp_f32_e64 v55, -v43
	v_pk_add_f32 v[56:57], v[56:57], 1.0 op_sel_hi:[1,0]
	v_pk_add_f32 v[52:53], v[52:53], 1.0 op_sel_hi:[1,0]
	v_pk_add_f32 v[58:59], v[58:59], 1.0 op_sel_hi:[1,0]
	v_pk_add_f32 v[54:55], v[54:55], 1.0 op_sel_hi:[1,0]
	v_rcp_f32_e32 v52, v52
	v_rcp_f32_e32 v54, v54
	v_rcp_f32_e32 v53, v53
	v_rcp_f32_e32 v55, v55
	v_rcp_f32_e32 v56, v56
	v_rcp_f32_e32 v58, v58
	v_rcp_f32_e32 v57, v57
	v_rcp_f32_e32 v59, v59
	v_add_u32_e32 v50, 0x90, v158
	v_pk_mul_f32 v[40:41], v[48:49], v[40:41]
	v_pk_mul_f32 v[38:39], v[46:47], v[38:39]
	v_pk_mul_f32 v[36:37], v[44:45], v[36:37]
	v_pk_mul_f32 v[34:35], v[42:43], v[34:35]
	v_mad_i64_i32 v[50:51], s[40:41], v50, s38, v[140:141]
	v_pk_mul_f32 v[40:41], v[56:57], v[40:41]
	v_pk_mul_f32 v[38:39], v[52:53], v[38:39]
	v_pk_mul_f32 v[42:43], v[58:59], v[36:37]
	v_pk_mul_f32 v[36:37], v[54:55], v[34:35]
	v_lshl_add_u64 v[50:51], v[50:51], 0, v[142:143]
	v_cvt_pk_bf16_f32 v34, v38, v39
	v_cvt_pk_bf16_f32 v35, v40, v41
	v_cvt_pk_bf16_f32 v36, v36, v37
	v_cvt_pk_bf16_f32 v37, v42, v43
	global_store_dwordx4 v[50:51], v[34:37], off nt
	v_exp_f32_e64 v38, -v26
	v_exp_f32_e64 v40, -v32
	v_exp_f32_e64 v36, -v30
	v_exp_f32_e64 v37, -v31
	v_exp_f32_e64 v41, -v33
	v_exp_f32_e64 v42, -v28
	v_exp_f32_e64 v43, -v29
	v_exp_f32_e64 v39, -v27
	v_pk_add_f32 v[40:41], v[40:41], 1.0 op_sel_hi:[1,0]
	v_pk_add_f32 v[36:37], v[36:37], 1.0 op_sel_hi:[1,0]
	v_pk_add_f32 v[42:43], v[42:43], 1.0 op_sel_hi:[1,0]
	v_pk_add_f32 v[38:39], v[38:39], 1.0 op_sel_hi:[1,0]
	v_rcp_f32_e32 v36, v36
	v_rcp_f32_e32 v38, v38
	v_rcp_f32_e32 v37, v37
	v_rcp_f32_e32 v39, v39
	v_rcp_f32_e32 v40, v40
	v_rcp_f32_e32 v42, v42
	v_rcp_f32_e32 v41, v41
	v_rcp_f32_e32 v43, v43
	v_add_u32_e32 v34, 0xa0, v158
	v_pk_mul_f32 v[24:25], v[32:33], v[24:25]
	v_pk_mul_f32 v[22:23], v[30:31], v[22:23]
	v_pk_mul_f32 v[20:21], v[28:29], v[20:21]
	v_pk_mul_f32 v[18:19], v[26:27], v[18:19]
	v_mad_i64_i32 v[34:35], s[40:41], v34, s38, v[140:141]
	v_pk_mul_f32 v[24:25], v[40:41], v[24:25]
	v_pk_mul_f32 v[22:23], v[36:37], v[22:23]
	v_pk_mul_f32 v[26:27], v[42:43], v[20:21]
	v_pk_mul_f32 v[20:21], v[38:39], v[18:19]
	v_lshl_add_u64 v[34:35], v[34:35], 0, v[142:143]
	v_cvt_pk_bf16_f32 v18, v22, v23
	v_cvt_pk_bf16_f32 v19, v24, v25
	v_cvt_pk_bf16_f32 v20, v20, v21
	v_cvt_pk_bf16_f32 v21, v26, v27
	global_store_dwordx4 v[34:35], v[18:21], off nt
	v_exp_f32_e64 v22, -v10
	v_exp_f32_e64 v24, -v16
	v_exp_f32_e64 v20, -v14
	v_exp_f32_e64 v21, -v15
	v_exp_f32_e64 v25, -v17
	v_exp_f32_e64 v26, -v12
	v_exp_f32_e64 v27, -v13
	v_exp_f32_e64 v23, -v11
	v_pk_add_f32 v[24:25], v[24:25], 1.0 op_sel_hi:[1,0]
	v_pk_add_f32 v[20:21], v[20:21], 1.0 op_sel_hi:[1,0]
	v_pk_add_f32 v[26:27], v[26:27], 1.0 op_sel_hi:[1,0]
	v_pk_add_f32 v[22:23], v[22:23], 1.0 op_sel_hi:[1,0]
	v_rcp_f32_e32 v20, v20
	v_rcp_f32_e32 v22, v22
	v_rcp_f32_e32 v21, v21
	v_rcp_f32_e32 v23, v23
	v_rcp_f32_e32 v24, v24
	v_rcp_f32_e32 v26, v26
	v_rcp_f32_e32 v25, v25
	v_rcp_f32_e32 v27, v27
	v_add_u32_e32 v18, 0xb0, v158
	v_pk_mul_f32 v[8:9], v[16:17], v[8:9]
	v_pk_mul_f32 v[6:7], v[14:15], v[6:7]
	v_pk_mul_f32 v[4:5], v[12:13], v[4:5]
	v_pk_mul_f32 v[2:3], v[10:11], v[2:3]
	v_mad_i64_i32 v[18:19], s[40:41], v18, s38, v[140:141]
	v_pk_mul_f32 v[8:9], v[24:25], v[8:9]
	v_pk_mul_f32 v[6:7], v[20:21], v[6:7]
	v_pk_mul_f32 v[10:11], v[26:27], v[4:5]
	v_pk_mul_f32 v[4:5], v[22:23], v[2:3]
	v_lshl_add_u64 v[18:19], v[18:19], 0, v[142:143]
	v_cvt_pk_bf16_f32 v2, v6, v7
	v_cvt_pk_bf16_f32 v3, v8, v9
	v_cvt_pk_bf16_f32 v4, v4, v5
	v_cvt_pk_bf16_f32 v5, v10, v11
	s_andn2_b64 vcc, exec, s[4:5]
	s_mov_b64 s[4:5], -1
	global_store_dwordx4 v[18:19], v[2:5], off nt
	s_cbranch_vccnz .LBB0_509
	s_andn2_b64 vcc, exec, s[6:7]
	s_cbranch_vccnz .LBB0_508
	s_branch .LBB0_508
